# grid barrier: non-leader workgroups poll the cross-XCD release generation directly (one hop less per barrier)
# baseline (speedup 1.0000x reference)
.LBB0_333:
	s_or_b64 exec, exec, s[14:15]
	v_cvt_f32_u32_e32 v4, v2
	s_waitcnt vmcnt(0)
	v_readfirstlane_b32 s1, v3
	v_sub_u32_e32 v3, 0, v2
	v_rcp_iflag_f32_e32 v4, v4
	v_add_u32_e32 v5, s1, v1
	v_mul_f32_e32 v4, 0x4f7ffffe, v4
	v_cvt_u32_f32_e32 v4, v4
	v_mul_lo_u32 v1, v3, v4
	v_mul_hi_u32 v1, v4, v1
	v_add_u32_e32 v1, v4, v1
	v_mul_hi_u32 v1, v5, v1
	v_mul_lo_u32 v3, v1, v2
	v_sub_u32_e32 v3, v5, v3
	v_add_u32_e32 v4, 1, v1
	v_cmp_ge_u32_e32 vcc, v3, v2
	s_nop 1
	v_cndmask_b32_e32 v1, v1, v4, vcc
	v_sub_u32_e32 v4, v3, v2
	v_cndmask_b32_e32 v3, v3, v4, vcc
	v_add_u32_e32 v4, 1, v1
	v_cmp_ge_u32_e32 vcc, v3, v2
	v_add_u32_e32 v3, 1, v5
	s_nop 0
	v_cndmask_b32_e32 v1, v1, v4, vcc
	v_mul_lo_u32 v4, v2, v1
	v_add_u32_e32 v2, v4, v2
	v_cmp_ne_u32_e32 vcc, v3, v2
	s_and_saveexec_b64 s[12:13], vcc
	s_xor_b64 s[12:13], exec, s[12:13]
	s_cbranch_execz .LBB0_347
	s_waitcnt lgkmcnt(0)
	v_mov_b32_e32 v0, 0x7100
	global_load_dword v0, v0, s[8:9] offset:1024 sc1
	s_add_u32 s18, s8, 0x7500
	s_addc_u32 s19, s9, 0
	s_waitcnt vmcnt(0)
	v_cmp_eq_u32_e32 vcc, v0, v1
	s_and_saveexec_b64 s[14:15], vcc
	s_cbranch_execz .LBB0_346
	s_add_u32 s16, s8, 0x4200
	s_addc_u32 s17, s9, 0
	s_mov_b32 s1, 1
	s_mov_b64 s[20:21], 0
	v_mov_b32_e32 v0, 0
	s_branch .LBB0_337

.LBB0_396:
	s_or_b64 exec, exec, s[12:13]
	v_cvt_f32_u32_e32 v5, v3
	s_waitcnt vmcnt(0)
	v_readfirstlane_b32 s0, v4
	v_sub_u32_e32 v4, 0, v3
	v_rcp_iflag_f32_e32 v5, v5
	v_add_u32_e32 v6, s0, v0
	v_mul_f32_e32 v5, 0x4f7ffffe, v5
	v_cvt_u32_f32_e32 v5, v5
	v_mul_lo_u32 v0, v4, v5
	v_mul_hi_u32 v0, v5, v0
	v_add_u32_e32 v0, v5, v0
	v_mul_hi_u32 v0, v6, v0
	v_mul_lo_u32 v4, v0, v3
	v_sub_u32_e32 v4, v6, v4
	v_add_u32_e32 v5, 1, v0
	v_cmp_ge_u32_e32 vcc, v4, v3
	s_nop 1
	v_cndmask_b32_e32 v0, v0, v5, vcc
	v_sub_u32_e32 v5, v4, v3
	v_cndmask_b32_e32 v4, v4, v5, vcc
	v_add_u32_e32 v5, 1, v0
	v_cmp_ge_u32_e32 vcc, v4, v3
	v_add_u32_e32 v4, 1, v6
	s_nop 0
	v_cndmask_b32_e32 v0, v0, v5, vcc
	v_mul_lo_u32 v5, v3, v0
	v_add_u32_e32 v3, v5, v3
	v_cmp_ne_u32_e32 vcc, v4, v3
	s_and_saveexec_b64 s[10:11], vcc
	s_xor_b64 s[10:11], exec, s[10:11]
	s_cbranch_execz .LBB0_410
	s_waitcnt lgkmcnt(0)
	v_mov_b32_e32 v2, 0x7100
	global_load_dword v2, v2, s[6:7] offset:1024 sc1
	s_add_u32 s16, s6, 0x7500
	s_addc_u32 s17, s7, 0
	s_waitcnt vmcnt(0)
	v_cmp_eq_u32_e32 vcc, v2, v0
	s_and_saveexec_b64 s[12:13], vcc
	s_cbranch_execz .LBB0_409
	s_add_u32 s14, s6, 0x4200
	s_addc_u32 s15, s7, 0
	s_mov_b32 s0, 1
	s_mov_b64 s[18:19], 0
	s_branch .LBB0_400

.LBB0_1361:
	s_or_b64 exec, exec, s[16:17]
	v_cvt_f32_u32_e32 v5, v3
	s_waitcnt vmcnt(0)
	v_readfirstlane_b32 s0, v4
	v_sub_u32_e32 v4, 0, v3
	v_rcp_iflag_f32_e32 v5, v5
	v_add_u32_e32 v6, s0, v0
	v_mul_f32_e32 v5, 0x4f7ffffe, v5
	v_cvt_u32_f32_e32 v5, v5
	v_mul_lo_u32 v0, v4, v5
	v_mul_hi_u32 v0, v5, v0
	v_add_u32_e32 v0, v5, v0
	v_mul_hi_u32 v0, v6, v0
	v_mul_lo_u32 v4, v0, v3
	v_sub_u32_e32 v4, v6, v4
	v_add_u32_e32 v5, 1, v0
	v_cmp_ge_u32_e32 vcc, v4, v3
	s_nop 1
	v_cndmask_b32_e32 v0, v0, v5, vcc
	v_sub_u32_e32 v5, v4, v3
	v_cndmask_b32_e32 v4, v4, v5, vcc
	v_add_u32_e32 v5, 1, v0
	v_cmp_ge_u32_e32 vcc, v4, v3
	v_add_u32_e32 v4, 1, v6
	s_nop 0
	v_cndmask_b32_e32 v0, v0, v5, vcc
	v_mul_lo_u32 v5, v3, v0
	v_add_u32_e32 v3, v5, v3
	v_cmp_ne_u32_e32 vcc, v4, v3
	s_and_saveexec_b64 s[14:15], vcc
	s_xor_b64 s[14:15], exec, s[14:15]
	s_cbranch_execz .LBB0_1375
	s_waitcnt lgkmcnt(0)
	v_mov_b32_e32 v2, 0x7100
	global_load_dword v2, v2, s[8:9] offset:1024 sc1
	s_add_u32 s20, s8, 0x7500
	s_addc_u32 s21, s9, 0
	s_waitcnt vmcnt(0)
	v_cmp_eq_u32_e32 vcc, v2, v0
	s_and_saveexec_b64 s[16:17], vcc
	s_cbranch_execz .LBB0_1374
	s_add_u32 s18, s8, 0x4200
	s_addc_u32 s19, s9, 0
	s_mov_b32 s0, 1
	s_mov_b64 s[22:23], 0
	s_branch .LBB0_1365
